# baseline (speedup 1.0000x reference)
; #define GAS __attribute__((address_space(1)))
;     ...
;       {
;         const int ck = tid & 15;
;         const int ch = chb + ck * 8;
;         float w0[2][8], w1[2][8], w2[2][8], bb[2][8];
; #pragma unroll
;         for (int h = 0; h < 2; ++h) {
;           ld8f(p->w_conv + ch + h * DFF, w0[h]); ld8f(p->w_conv + UPW + ch + h * DFF, w1[h]);
;           ld8f(p->w_conv + 2 * UPW + ch + h * DFF, w2[h]); ld8f(p->b_conv + ch + h * DFF, bb[h]);
;         }
;         u16* FI = (u16*)(wsl + w_fi);
; #pragma unroll 2
;         for (int i = 0; i < 8; ++i) {
;           const int row = (tid >> 4) + i * 32;
;           const int rg = g0 + cur_brow + row;
;           int t, b; const bool samp = rg >= NPROMPT;
;           if (!samp) { t = rg & (SEQ - 1); b = rg >> 11; } else { const int rs = rg - NPROMPT; t = rs & (DSEQ - 1); b = rs >> 6; }
;           if (t >= 2 && row < 2) continue;
;           float res[8];
; #pragma unroll
;           for (int h = 0; h < 2; ++h) {
;             const int c16 = h * 16 + ck;
;             float cur[8], p1[8], p2[8];
;             ld8(reinterpret_cast<const u16*>(st + row * 512 + ((c16 ^ (row & 31)) << 4)), cur);
;             if (t >= 1) ld8(reinterpret_cast<const u16*>(st + (row - 1) * 512 + ((c16 ^ ((row - 1) & 31)) << 4)), p1);
;             else if (samp) ld8f(p->cstate + ((size_t)b * 2 + 1) * UPW + ch + h * DFF, p1);
;             else { for (int k = 0; k < 8; ++k) p1[k] = 0.f; }
;             if (t >= 2) ld8(reinterpret_cast<const u16*>(st + (row - 2) * 512 + ((c16 ^ ((row - 2) & 31)) << 4)), p2);
;             else if (samp) ld8f(p->cstate + ((size_t)b * 2 + t) * UPW + ch + h * DFF, p2);
;             else { for (int k = 0; k < 8; ++k) p2[k] = 0.f; }
; #pragma unroll
;             for (int k = 0; k < 8; ++k) {
;               float cv = bb[h][k] + w0[h][k] * p2[k] + w1[h][k] * p1[k] + w2[h][k] * cur[k];
;               if (h == 0) res[k] = gelu_f(cv); else res[k] *= cv;
;             }
;           }
;           *(GAS uint4*)(FI + (size_t)(cur_brow + row) * DFF + ch) =
;               make_uint4(pack2(res[0], res[1]), pack2(res[2], res[3]), pack2(res[4], res[5]), pack2(res[6], res[7]));
;         }
;     ...
;       if (has_next) PROLOGUE_ISSUE(brow, bcol);
.Lupc_fast_p:
	s_load_dwordx4 s[4:7], s[0:1], 0x98
	v_and_b32_e32 v140, 15, v149
	v_lshrrev_b32_e32 v141, 4, v149
	s_lshr_b32 s20, s70, 1
	s_and_b32 s20, s20, 0xffffff80
	v_lshlrev_b32_e32 v142, 3, v141
	v_lshl_add_u32 v143, v140, 3, s20
	v_lshlrev_b32_e32 v143, 2, v143
	s_waitcnt lgkmcnt(0)
	s_add_u32 s8, s4, 0x2c00
	s_addc_u32 s9, s5, 0
	s_add_u32 s10, s4, 0x5800
	s_addc_u32 s11, s5, 0
	s_add_u32 s12, s4, 0x8400
	s_addc_u32 s13, s5, 0
	s_add_u32 s14, s4, 0xb000
	s_addc_u32 s15, s5, 0
	s_add_u32 s16, s4, 0xdc00
	s_addc_u32 s17, s5, 0
	s_add_u32 s18, s6, 0x2c00
	s_addc_u32 s19, s7, 0
	global_load_dwordx4 v[2:5], v143, s[4:5]
	global_load_dwordx4 v[6:9], v143, s[4:5] offset:16
	global_load_dwordx4 v[10:13], v143, s[8:9]
	global_load_dwordx4 v[14:17], v143, s[8:9] offset:16
	global_load_dwordx4 v[18:21], v143, s[10:11]
	global_load_dwordx4 v[22:25], v143, s[10:11] offset:16
	global_load_dwordx4 v[26:29], v143, s[12:13]
	global_load_dwordx4 v[30:33], v143, s[12:13] offset:16
	global_load_dwordx4 v[34:37], v143, s[14:15]
	global_load_dwordx4 v[38:41], v143, s[14:15] offset:16
	global_load_dwordx4 v[42:45], v143, s[16:17]
	global_load_dwordx4 v[46:49], v143, s[16:17] offset:16
	global_load_dwordx4 v[50:53], v143, s[6:7]
	global_load_dwordx4 v[54:57], v143, s[6:7] offset:16
	global_load_dwordx4 v[58:61], v143, s[18:19]
	global_load_dwordx4 v[62:65], v143, s[18:19] offset:16
	s_mul_i32 s22, s86, 0x1600
	s_lshl_b32 s23, s20, 1
	s_add_u32 s22, s22, s23
	s_add_u32 s22, s22, 0x1aac0000
	s_add_u32 s22, s74, s22
	s_addc_u32 s23, s75, 0
	v_mul_u32_u24_e32 v144, 0x1600, v142
	v_lshl_add_u32 v144, v140, 4, v144
	s_mov_b32 s21, 0xffff0000
	s_mov_b32 s67, 0xbdd2d3e7
	v_cmp_lt_u32_e64 s[58:59], 15, v149
	v_add_u32_e32 v145, -2, v142
	v_max_i32_e32 v145, 0, v145
	v_and_b32_e32 v146, 31, v145
	v_xor_b32_e32 v146, v146, v140
	v_lshlrev_b32_e32 v146, 4, v146
	v_lshl_or_b32 v146, v145, 9, v146
	v_xor_b32_e32 v147, 0x100, v146
	ds_read_b128 v[66:69], v146
	ds_read_b128 v[70:73], v147
	v_add_u32_e32 v145, -1, v142
	v_max_i32_e32 v145, 0, v145
	v_and_b32_e32 v146, 31, v145
	v_xor_b32_e32 v146, v146, v140
	v_lshlrev_b32_e32 v146, 4, v146
	v_lshl_or_b32 v146, v145, 9, v146
	v_xor_b32_e32 v147, 0x100, v146
	ds_read_b128 v[74:77], v146
	ds_read_b128 v[78:81], v147
	v_mov_b32_e32 v145, v142
	v_and_b32_e32 v146, 31, v145
	v_xor_b32_e32 v146, v146, v140
	v_lshlrev_b32_e32 v146, 4, v146
	v_lshl_or_b32 v146, v145, 9, v146
	v_xor_b32_e32 v147, 0x100, v146
	ds_read_b128 v[82:85], v146
	ds_read_b128 v[86:89], v147
	v_add_u32_e32 v145, 1, v142
	v_and_b32_e32 v146, 31, v145
	v_xor_b32_e32 v146, v146, v140
	v_lshlrev_b32_e32 v146, 4, v146
	v_lshl_or_b32 v146, v145, 9, v146
	v_xor_b32_e32 v147, 0x100, v146
	ds_read_b128 v[90:93], v146
	ds_read_b128 v[94:97], v147
	v_add_u32_e32 v145, 2, v142
	v_and_b32_e32 v146, 31, v145
	v_xor_b32_e32 v146, v146, v140
	v_lshlrev_b32_e32 v146, 4, v146
	v_lshl_or_b32 v146, v145, 9, v146
	v_xor_b32_e32 v147, 0x100, v146
	ds_read_b128 v[98:101], v146
	ds_read_b128 v[102:105], v147
	v_add_u32_e32 v145, 3, v142
	v_and_b32_e32 v146, 31, v145
	v_xor_b32_e32 v146, v146, v140
	v_lshlrev_b32_e32 v146, 4, v146
	v_lshl_or_b32 v146, v145, 9, v146
	v_xor_b32_e32 v147, 0x100, v146
	ds_read_b128 v[106:109], v146
	ds_read_b128 v[110:113], v147
	v_add_u32_e32 v145, 4, v142
	v_and_b32_e32 v146, 31, v145
	v_xor_b32_e32 v146, v146, v140
	v_lshlrev_b32_e32 v146, 4, v146
	v_lshl_or_b32 v146, v145, 9, v146
	v_xor_b32_e32 v147, 0x100, v146
	ds_read_b128 v[114:117], v146
	ds_read_b128 v[118:121], v147
	v_add_u32_e32 v145, 5, v142
	v_and_b32_e32 v146, 31, v145
	v_xor_b32_e32 v146, v146, v140
	v_lshlrev_b32_e32 v146, 4, v146
	v_lshl_or_b32 v146, v145, 9, v146
	v_xor_b32_e32 v147, 0x100, v146
	ds_read_b128 v[122:125], v146
	ds_read_b128 v[126:129], v147
	s_waitcnt lgkmcnt(12)
	v_lshlrev_b32_e32 v150, 16, v66
	v_and_b32_e32 v151, s21, v66
	v_lshlrev_b32_e32 v152, 16, v67
	v_and_b32_e32 v153, s21, v67
	v_lshlrev_b32_e32 v154, 16, v68
	v_and_b32_e32 v155, s21, v68
	v_lshlrev_b32_e32 v156, 16, v69
	v_and_b32_e32 v157, s21, v69
	v_lshlrev_b32_e32 v158, 16, v70
	v_and_b32_e32 v159, s21, v70
	v_lshlrev_b32_e32 v160, 16, v71
	v_and_b32_e32 v161, s21, v71
	v_lshlrev_b32_e32 v162, 16, v72
	v_and_b32_e32 v163, s21, v72
	v_lshlrev_b32_e32 v164, 16, v73
	v_and_b32_e32 v165, s21, v73
	v_lshlrev_b32_e32 v166, 16, v74
	v_and_b32_e32 v167, s21, v74
	v_lshlrev_b32_e32 v168, 16, v75
	v_and_b32_e32 v169, s21, v75
	v_lshlrev_b32_e32 v170, 16, v76
	v_and_b32_e32 v171, s21, v76
	v_lshlrev_b32_e32 v172, 16, v77
	v_and_b32_e32 v173, s21, v77
	v_lshlrev_b32_e32 v174, 16, v78
	v_and_b32_e32 v175, s21, v78
	v_lshlrev_b32_e32 v176, 16, v79
	v_and_b32_e32 v177, s21, v79
	v_lshlrev_b32_e32 v178, 16, v80
	v_and_b32_e32 v179, s21, v80
	v_lshlrev_b32_e32 v180, 16, v81
	v_and_b32_e32 v181, s21, v81
	v_add_u32_e32 v145, 6, v142
	v_and_b32_e32 v146, 31, v145
	v_xor_b32_e32 v146, v146, v140
	v_lshlrev_b32_e32 v146, 4, v146
	v_lshl_or_b32 v146, v145, 9, v146
	v_xor_b32_e32 v147, 0x100, v146
	ds_read_b128 v[66:69], v146
	ds_read_b128 v[70:73], v147
	v_add_u32_e32 v145, 7, v142
	v_and_b32_e32 v146, 31, v145
	v_xor_b32_e32 v146, v146, v140
	v_lshlrev_b32_e32 v146, 4, v146
	v_lshl_or_b32 v146, v145, 9, v146
	v_xor_b32_e32 v147, 0x100, v146
	ds_read_b128 v[74:77], v146
	ds_read_b128 v[78:81], v147
	s_waitcnt lgkmcnt(0)
	s_barrier
	s_and_b64 vcc, exec, s[56:57]
	s_cbranch_vccz .Lupc_nonext_p
; #define GAS __attribute__((address_space(1)))
;     ...
; #pragma unroll
;           for (int h = 0; h < 2; ++h) {
;             const int c16 = h * 16 + ck;
;             float cur[8], p1[8], p2[8];
;             ld8(reinterpret_cast<const u16*>(st + row * 512 + ((c16 ^ (row & 31)) << 4)), cur);
;             if (t >= 1) ld8(reinterpret_cast<const u16*>(st + (row - 1) * 512 + ((c16 ^ ((row - 1) & 31)) << 4)), p1);
;             else if (samp) ld8f(p->cstate + ((size_t)b * 2 + 1) * UPW + ch + h * DFF, p1);
;             else { for (int k = 0; k < 8; ++k) p1[k] = 0.f; }
;             if (t >= 2) ld8(reinterpret_cast<const u16*>(st + (row - 2) * 512 + ((c16 ^ ((row - 2) & 31)) << 4)), p2);
;             else if (samp) ld8f(p->cstate + ((size_t)b * 2 + t) * UPW + ch + h * DFF, p2);
;             else { for (int k = 0; k < 8; ++k) p2[k] = 0.f; }
; #pragma unroll
;             for (int k = 0; k < 8; ++k) {
;               float cv = bb[h][k] + w0[h][k] * p2[k] + w1[h][k] * p1[k] + w2[h][k] * cur[k];
;               if (h == 0) res[k] = gelu_f(cv); else res[k] *= cv;
;             }
;           }
;           *(GAS uint4*)(FI + (size_t)(cur_brow + row) * DFF + ch) =
;               make_uint4(pack2(res[0], res[1]), pack2(res[2], res[3]), pack2(res[4], res[5]), pack2(res[6], res[7]));
	s_mul_hi_i32 s3, s82, s34
	s_mul_i32 s2, s82, s34
	s_lshl_b64 s[2:3], s[2:3], 1
	s_add_u32 s2, s54, s2
	s_addc_u32 s3, s55, s3
	v_lshl_add_u64 v[230:231], s[2:3], 0, v[132:133]
	v_lshl_add_u64 v[232:233], s[2:3], 0, v[134:135]
	s_mul_hi_i32 s3, s87, s34
	s_mul_i32 s2, s87, s34
	s_lshl_b64 s[2:3], s[2:3], 1
	s_add_u32 s2, s52, s2
	s_addc_u32 s3, s53, s3
	v_lshl_add_u64 v[234:235], s[2:3], 0, v[132:133]
	v_lshl_add_u64 v[236:237], s[2:3], 0, v[134:135]
	s_or_b32 s2, s82, 0x80
	s_mul_hi_i32 s3, s2, s34
	s_mul_i32 s2, s2, s34
	s_lshl_b64 s[2:3], s[2:3], 1
	s_add_u32 s2, s54, s2
	s_mov_b32 m0, s39
	s_addc_u32 s3, s55, s3
	global_load_lds_dwordx4 v[230:231], off
	s_mov_b32 m0, s40
	v_lshl_add_u64 v[238:239], s[2:3], 0, v[132:133]
	v_lshl_add_u64 v[240:241], s[2:3], 0, v[134:135]
	s_or_b32 s2, s87, 0x80
	global_load_lds_dwordx4 v[232:233], off
	s_mov_b32 m0, s24
	s_mul_hi_i32 s3, s2, s34
	s_mul_i32 s2, s2, s34
	global_load_lds_dwordx4 v[234:235], off
	s_mov_b32 m0, s41
	s_lshl_b64 s[2:3], s[2:3], 1
	global_load_lds_dwordx4 v[236:237], off
	s_mov_b32 m0, s62
	s_add_u32 s2, s52, s2
	global_load_lds_dwordx4 v[238:239], off
	s_mov_b32 m0, s44
	s_addc_u32 s3, s53, s3
	global_load_lds_dwordx4 v[240:241], off
	v_lshl_add_u64 v[242:243], s[2:3], 0, v[132:133]
	s_mov_b32 m0, s45
	v_lshl_add_u64 v[230:231], v[230:231], 0, s[90:91]
	global_load_lds_dwordx4 v[242:243], off
	v_lshl_add_u64 v[242:243], s[2:3], 0, v[134:135]
	s_mov_b32 m0, s38
	s_mov_b32 s8, 34
	global_load_lds_dwordx4 v[242:243], off
	s_mov_b32 m0, s28
	s_nop 0
	global_load_lds_dwordx4 v[230:231], off
	v_lshl_add_u64 v[230:231], v[232:233], 0, s[90:91]
	s_mov_b32 m0, s29
	s_nop 0
	global_load_lds_dwordx4 v[230:231], off
	v_lshl_add_u64 v[230:231], v[234:235], 0, s[90:91]
	s_mov_b32 m0, s36
	s_nop 0
	global_load_lds_dwordx4 v[230:231], off
	v_lshl_add_u64 v[230:231], v[236:237], 0, s[90:91]
	s_mov_b32 m0, s37
	s_nop 0
	global_load_lds_dwordx4 v[230:231], off
	v_lshl_add_u64 v[230:231], v[238:239], 0, s[90:91]
	s_mov_b32 m0, s26
	s_nop 0
	global_load_lds_dwordx4 v[230:231], off
	v_lshl_add_u64 v[230:231], v[240:241], 0, s[90:91]
	s_mov_b32 m0, s27
	s_nop 0
	global_load_lds_dwordx4 v[230:231], off
	s_waitcnt vmcnt(14)
	s_branch .Lupc_compute_p
.Lupc_nonext_p:
	s_mov_b32 s8, 35
	s_waitcnt vmcnt(0)
.Lupc_compute_p:
	v_lshlrev_b32_e32 v214, 16, v82
	v_and_b32_e32 v215, s21, v82
	v_lshlrev_b32_e32 v216, 16, v83
	v_and_b32_e32 v217, s21, v83
	v_lshlrev_b32_e32 v218, 16, v84
	v_and_b32_e32 v219, s21, v84
	v_lshlrev_b32_e32 v220, 16, v85
	v_and_b32_e32 v221, s21, v85
	v_lshlrev_b32_e32 v222, 16, v86
	v_and_b32_e32 v223, s21, v86
	v_lshlrev_b32_e32 v224, 16, v87
	v_and_b32_e32 v225, s21, v87
	v_lshlrev_b32_e32 v226, 16, v88
	v_and_b32_e32 v227, s21, v88
	v_lshlrev_b32_e32 v228, 16, v89
	v_and_b32_e32 v229, s21, v89
	v_pk_fma_f32 v[230:231], v[2:3], v[150:151], v[50:51]
	v_pk_fma_f32 v[232:233], v[4:5], v[152:153], v[52:53]
	v_pk_fma_f32 v[234:235], v[6:7], v[154:155], v[54:55]
	v_pk_fma_f32 v[236:237], v[8:9], v[156:157], v[56:57]
	v_pk_fma_f32 v[238:239], v[10:11], v[158:159], v[58:59]
	v_pk_fma_f32 v[240:241], v[12:13], v[160:161], v[60:61]
	v_pk_fma_f32 v[242:243], v[14:15], v[162:163], v[62:63]
	v_pk_fma_f32 v[244:245], v[16:17], v[164:165], v[64:65]
	v_pk_fma_f32 v[230:231], v[18:19], v[166:167], v[230:231]
	v_pk_fma_f32 v[232:233], v[20:21], v[168:169], v[232:233]
	v_pk_fma_f32 v[234:235], v[22:23], v[170:171], v[234:235]
	v_pk_fma_f32 v[236:237], v[24:25], v[172:173], v[236:237]
	v_pk_fma_f32 v[238:239], v[26:27], v[174:175], v[238:239]
	v_pk_fma_f32 v[240:241], v[28:29], v[176:177], v[240:241]
	v_pk_fma_f32 v[242:243], v[30:31], v[178:179], v[242:243]
	v_pk_fma_f32 v[244:245], v[32:33], v[180:181], v[244:245]
	v_pk_fma_f32 v[230:231], v[34:35], v[214:215], v[230:231]
	v_pk_fma_f32 v[232:233], v[36:37], v[216:217], v[232:233]
	v_pk_fma_f32 v[234:235], v[38:39], v[218:219], v[234:235]
	v_pk_fma_f32 v[236:237], v[40:41], v[220:221], v[236:237]
	v_pk_fma_f32 v[238:239], v[42:43], v[222:223], v[238:239]
	v_pk_fma_f32 v[240:241], v[44:45], v[224:225], v[240:241]
	v_pk_fma_f32 v[242:243], v[46:47], v[226:227], v[242:243]
	v_pk_fma_f32 v[244:245], v[48:49], v[228:229], v[244:245]
	v_mul_f32_e32 v246, v230, v230
	v_mul_f32_e32 v247, v231, v231
	v_mul_f32_e32 v248, v232, v232
	v_mul_f32_e32 v249, v233, v233
	v_mul_f32_e32 v250, v234, v234
	v_mul_f32_e32 v251, v235, v235
	v_mul_f32_e32 v252, v236, v236
	v_mul_f32_e32 v253, v237, v237
	v_fma_f32 v246, v246, s67, v198
	v_fma_f32 v247, v247, s67, v198
	v_fma_f32 v248, v248, s67, v198
	v_fma_f32 v249, v249, s67, v198
	v_fma_f32 v250, v250, s67, v198
	v_fma_f32 v251, v251, s67, v198
	v_fma_f32 v252, v252, s67, v198
	v_fma_f32 v253, v253, s67, v198
	v_mul_f32_e32 v246, v230, v246
	v_mul_f32_e32 v247, v231, v247
	v_mul_f32_e32 v248, v232, v248
	v_mul_f32_e32 v249, v233, v249
	v_mul_f32_e32 v250, v234, v250
	v_mul_f32_e32 v251, v235, v251
	v_mul_f32_e32 v252, v236, v252
	v_mul_f32_e32 v253, v237, v253
	v_exp_f32_e32 v246, v246
	v_exp_f32_e32 v247, v247
	v_exp_f32_e32 v248, v248
	v_exp_f32_e32 v249, v249
	v_exp_f32_e32 v250, v250
	v_exp_f32_e32 v251, v251
	v_exp_f32_e32 v252, v252
	v_exp_f32_e32 v253, v253
	v_add_f32_e32 v246, 1.0, v246
	v_add_f32_e32 v247, 1.0, v247
	v_add_f32_e32 v248, 1.0, v248
	v_add_f32_e32 v249, 1.0, v249
	v_add_f32_e32 v250, 1.0, v250
	v_add_f32_e32 v251, 1.0, v251
	v_add_f32_e32 v252, 1.0, v252
	v_add_f32_e32 v253, 1.0, v253
	v_rcp_f32_e32 v246, v246
	v_rcp_f32_e32 v247, v247
	v_rcp_f32_e32 v248, v248
	v_rcp_f32_e32 v249, v249
	v_rcp_f32_e32 v250, v250
	v_rcp_f32_e32 v251, v251
	v_rcp_f32_e32 v252, v252
	v_rcp_f32_e32 v253, v253
; #define GAS __attribute__((address_space(1)))
;     ...
;         for (int i = 0; i < 8; ++i) {
;           const int row = (tid >> 4) + i * 32;
;           const int rg = g0 + cur_brow + row;
;           int t, b; const bool samp = rg >= NPROMPT;
;           if (!samp) { t = rg & (SEQ - 1); b = rg >> 11; } else { const int rs = rg - NPROMPT; t = rs & (DSEQ - 1); b = rs >> 6; }
;           if (t >= 2 && row < 2) continue;
;           float res[8];
; #pragma unroll
;           for (int h = 0; h < 2; ++h) {
;             const int c16 = h * 16 + ck;
;             float cur[8], p1[8], p2[8];
;             ld8(reinterpret_cast<const u16*>(st + row * 512 + ((c16 ^ (row & 31)) << 4)), cur);
;             if (t >= 1) ld8(reinterpret_cast<const u16*>(st + (row - 1) * 512 + ((c16 ^ ((row - 1) & 31)) << 4)), p1);
;             else if (samp) ld8f(p->cstate + ((size_t)b * 2 + 1) * UPW + ch + h * DFF, p1);
;             else { for (int k = 0; k < 8; ++k) p1[k] = 0.f; }
;             if (t >= 2) ld8(reinterpret_cast<const u16*>(st + (row - 2) * 512 + ((c16 ^ ((row - 2) & 31)) << 4)), p2);
;             else if (samp) ld8f(p->cstate + ((size_t)b * 2 + t) * UPW + ch + h * DFF, p2);
;             else { for (int k = 0; k < 8; ++k) p2[k] = 0.f; }
; #pragma unroll
;             for (int k = 0; k < 8; ++k) {
;               float cv = bb[h][k] + w0[h][k] * p2[k] + w1[h][k] * p1[k] + w2[h][k] * cur[k];
;               if (h == 0) res[k] = gelu_f(cv); else res[k] *= cv;
;             }
;           }
;           *(GAS uint4*)(FI + (size_t)(cur_brow + row) * DFF + ch) =
;               make_uint4(pack2(res[0], res[1]), pack2(res[2], res[3]), pack2(res[4], res[5]), pack2(res[6], res[7]));
	v_mul_f32_e32 v246, v230, v246
	v_mul_f32_e32 v247, v231, v247
	v_mul_f32_e32 v248, v232, v248
	v_mul_f32_e32 v249, v233, v249
	v_mul_f32_e32 v250, v234, v250
	v_mul_f32_e32 v251, v235, v251
	v_mul_f32_e32 v252, v236, v252
	v_mul_f32_e32 v253, v237, v253
	v_mul_f32_e32 v246, v246, v238
	v_mul_f32_e32 v247, v247, v239
	v_mul_f32_e32 v248, v248, v240
	v_mul_f32_e32 v249, v249, v241
	v_mul_f32_e32 v250, v250, v242
	v_mul_f32_e32 v251, v251, v243
	v_mul_f32_e32 v252, v252, v244
	v_mul_f32_e32 v253, v253, v245
	v_cvt_pk_bf16_f32 v190, v246, v247
	v_cvt_pk_bf16_f32 v191, v248, v249
	v_cvt_pk_bf16_f32 v192, v250, v251
	v_cvt_pk_bf16_f32 v193, v252, v253
	s_and_saveexec_b64 s[96:97], s[58:59]
	global_store_dwordx4 v144, v[190:193], s[22:23]
	s_mov_b64 exec, s[96:97]
	v_add_u32_e32 v144, 0x1600, v144
	v_lshlrev_b32_e32 v150, 16, v90
	v_and_b32_e32 v151, s21, v90
	v_lshlrev_b32_e32 v152, 16, v91
	v_and_b32_e32 v153, s21, v91
	v_lshlrev_b32_e32 v154, 16, v92
	v_and_b32_e32 v155, s21, v92
	v_lshlrev_b32_e32 v156, 16, v93
	v_and_b32_e32 v157, s21, v93
	v_lshlrev_b32_e32 v158, 16, v94
	v_and_b32_e32 v159, s21, v94
	v_lshlrev_b32_e32 v160, 16, v95
	v_and_b32_e32 v161, s21, v95
	v_lshlrev_b32_e32 v162, 16, v96
	v_and_b32_e32 v163, s21, v96
	v_lshlrev_b32_e32 v164, 16, v97
	v_and_b32_e32 v165, s21, v97
	v_pk_fma_f32 v[230:231], v[2:3], v[166:167], v[50:51]
	v_pk_fma_f32 v[232:233], v[4:5], v[168:169], v[52:53]
	v_pk_fma_f32 v[234:235], v[6:7], v[170:171], v[54:55]
	v_pk_fma_f32 v[236:237], v[8:9], v[172:173], v[56:57]
	v_pk_fma_f32 v[238:239], v[10:11], v[174:175], v[58:59]
	v_pk_fma_f32 v[240:241], v[12:13], v[176:177], v[60:61]
	v_pk_fma_f32 v[242:243], v[14:15], v[178:179], v[62:63]
	v_pk_fma_f32 v[244:245], v[16:17], v[180:181], v[64:65]
	v_pk_fma_f32 v[230:231], v[18:19], v[214:215], v[230:231]
	v_pk_fma_f32 v[232:233], v[20:21], v[216:217], v[232:233]
	v_pk_fma_f32 v[234:235], v[22:23], v[218:219], v[234:235]
	v_pk_fma_f32 v[236:237], v[24:25], v[220:221], v[236:237]
	v_pk_fma_f32 v[238:239], v[26:27], v[222:223], v[238:239]
	v_pk_fma_f32 v[240:241], v[28:29], v[224:225], v[240:241]
	v_pk_fma_f32 v[242:243], v[30:31], v[226:227], v[242:243]
	v_pk_fma_f32 v[244:245], v[32:33], v[228:229], v[244:245]
	v_pk_fma_f32 v[230:231], v[34:35], v[150:151], v[230:231]
	v_pk_fma_f32 v[232:233], v[36:37], v[152:153], v[232:233]
	v_pk_fma_f32 v[234:235], v[38:39], v[154:155], v[234:235]
	v_pk_fma_f32 v[236:237], v[40:41], v[156:157], v[236:237]
	v_pk_fma_f32 v[238:239], v[42:43], v[158:159], v[238:239]
	v_pk_fma_f32 v[240:241], v[44:45], v[160:161], v[240:241]
	v_pk_fma_f32 v[242:243], v[46:47], v[162:163], v[242:243]
	v_pk_fma_f32 v[244:245], v[48:49], v[164:165], v[244:245]
	v_mul_f32_e32 v246, v230, v230
	v_mul_f32_e32 v247, v231, v231
	v_mul_f32_e32 v248, v232, v232
	v_mul_f32_e32 v249, v233, v233
	v_mul_f32_e32 v250, v234, v234
	v_mul_f32_e32 v251, v235, v235
	v_mul_f32_e32 v252, v236, v236
	v_mul_f32_e32 v253, v237, v237
	v_fma_f32 v246, v246, s67, v198
	v_fma_f32 v247, v247, s67, v198
	v_fma_f32 v248, v248, s67, v198
	v_fma_f32 v249, v249, s67, v198
	v_fma_f32 v250, v250, s67, v198
	v_fma_f32 v251, v251, s67, v198
	v_fma_f32 v252, v252, s67, v198
	v_fma_f32 v253, v253, s67, v198
	v_mul_f32_e32 v246, v230, v246
	v_mul_f32_e32 v247, v231, v247
	v_mul_f32_e32 v248, v232, v248
	v_mul_f32_e32 v249, v233, v249
	v_mul_f32_e32 v250, v234, v250
	v_mul_f32_e32 v251, v235, v251
	v_mul_f32_e32 v252, v236, v252
	v_mul_f32_e32 v253, v237, v253
	v_exp_f32_e32 v246, v246
	v_exp_f32_e32 v247, v247
	v_exp_f32_e32 v248, v248
	v_exp_f32_e32 v249, v249
	v_exp_f32_e32 v250, v250
	v_exp_f32_e32 v251, v251
	v_exp_f32_e32 v252, v252
	v_exp_f32_e32 v253, v253
	v_add_f32_e32 v246, 1.0, v246
	v_add_f32_e32 v247, 1.0, v247
	v_add_f32_e32 v248, 1.0, v248
	v_add_f32_e32 v249, 1.0, v249
	v_add_f32_e32 v250, 1.0, v250
	v_add_f32_e32 v251, 1.0, v251
	v_add_f32_e32 v252, 1.0, v252
	v_add_f32_e32 v253, 1.0, v253
	v_rcp_f32_e32 v246, v246
	v_rcp_f32_e32 v247, v247
	v_rcp_f32_e32 v248, v248
	v_rcp_f32_e32 v249, v249
	v_rcp_f32_e32 v250, v250
	v_rcp_f32_e32 v251, v251
	v_rcp_f32_e32 v252, v252
	v_rcp_f32_e32 v253, v253
	v_mul_f32_e32 v246, v230, v246
	v_mul_f32_e32 v247, v231, v247
	v_mul_f32_e32 v248, v232, v248
	v_mul_f32_e32 v249, v233, v249
	v_mul_f32_e32 v250, v234, v250
	v_mul_f32_e32 v251, v235, v251
	v_mul_f32_e32 v252, v236, v252
	v_mul_f32_e32 v253, v237, v253
	v_mul_f32_e32 v246, v246, v238
	v_mul_f32_e32 v247, v247, v239
	v_mul_f32_e32 v248, v248, v240
	v_mul_f32_e32 v249, v249, v241
	v_mul_f32_e32 v250, v250, v242
	v_mul_f32_e32 v251, v251, v243
	v_mul_f32_e32 v252, v252, v244
	v_mul_f32_e32 v253, v253, v245
	v_cvt_pk_bf16_f32 v190, v246, v247
	v_cvt_pk_bf16_f32 v191, v248, v249
	v_cvt_pk_bf16_f32 v192, v250, v251
	v_cvt_pk_bf16_f32 v193, v252, v253
	s_and_saveexec_b64 s[96:97], s[58:59]
	global_store_dwordx4 v144, v[190:193], s[22:23]
	s_mov_b64 exec, s[96:97]
	v_add_u32_e32 v144, 0x1600, v144
	v_lshlrev_b32_e32 v166, 16, v98
	v_and_b32_e32 v167, s21, v98
	v_lshlrev_b32_e32 v168, 16, v99
	v_and_b32_e32 v169, s21, v99
	v_lshlrev_b32_e32 v170, 16, v100
	v_and_b32_e32 v171, s21, v100
	v_lshlrev_b32_e32 v172, 16, v101
	v_and_b32_e32 v173, s21, v101
	v_lshlrev_b32_e32 v174, 16, v102
	v_and_b32_e32 v175, s21, v102
	v_lshlrev_b32_e32 v176, 16, v103
	v_and_b32_e32 v177, s21, v103
	v_lshlrev_b32_e32 v178, 16, v104
	v_and_b32_e32 v179, s21, v104
	v_lshlrev_b32_e32 v180, 16, v105
	v_and_b32_e32 v181, s21, v105
	v_pk_fma_f32 v[230:231], v[2:3], v[214:215], v[50:51]
	v_pk_fma_f32 v[232:233], v[4:5], v[216:217], v[52:53]
	v_pk_fma_f32 v[234:235], v[6:7], v[218:219], v[54:55]
; #define GAS __attribute__((address_space(1)))
;     ...
;         for (int i = 0; i < 8; ++i) {
;           const int row = (tid >> 4) + i * 32;
;           const int rg = g0 + cur_brow + row;
;           int t, b; const bool samp = rg >= NPROMPT;
;           if (!samp) { t = rg & (SEQ - 1); b = rg >> 11; } else { const int rs = rg - NPROMPT; t = rs & (DSEQ - 1); b = rs >> 6; }
;           if (t >= 2 && row < 2) continue;
;           float res[8];
; #pragma unroll
;           for (int h = 0; h < 2; ++h) {
;             const int c16 = h * 16 + ck;
;             float cur[8], p1[8], p2[8];
;             ld8(reinterpret_cast<const u16*>(st + row * 512 + ((c16 ^ (row & 31)) << 4)), cur);
;             if (t >= 1) ld8(reinterpret_cast<const u16*>(st + (row - 1) * 512 + ((c16 ^ ((row - 1) & 31)) << 4)), p1);
;             else if (samp) ld8f(p->cstate + ((size_t)b * 2 + 1) * UPW + ch + h * DFF, p1);
;             else { for (int k = 0; k < 8; ++k) p1[k] = 0.f; }
;             if (t >= 2) ld8(reinterpret_cast<const u16*>(st + (row - 2) * 512 + ((c16 ^ ((row - 2) & 31)) << 4)), p2);
;             else if (samp) ld8f(p->cstate + ((size_t)b * 2 + t) * UPW + ch + h * DFF, p2);
;             else { for (int k = 0; k < 8; ++k) p2[k] = 0.f; }
; #pragma unroll
;             for (int k = 0; k < 8; ++k) {
;               float cv = bb[h][k] + w0[h][k] * p2[k] + w1[h][k] * p1[k] + w2[h][k] * cur[k];
;               if (h == 0) res[k] = gelu_f(cv); else res[k] *= cv;
;             }
;           }
;           *(GAS uint4*)(FI + (size_t)(cur_brow + row) * DFF + ch) =
;               make_uint4(pack2(res[0], res[1]), pack2(res[2], res[3]), pack2(res[4], res[5]), pack2(res[6], res[7]));
	v_pk_fma_f32 v[236:237], v[8:9], v[220:221], v[56:57]
	v_pk_fma_f32 v[238:239], v[10:11], v[222:223], v[58:59]
	v_pk_fma_f32 v[240:241], v[12:13], v[224:225], v[60:61]
	v_pk_fma_f32 v[242:243], v[14:15], v[226:227], v[62:63]
	v_pk_fma_f32 v[244:245], v[16:17], v[228:229], v[64:65]
	v_pk_fma_f32 v[230:231], v[18:19], v[150:151], v[230:231]
	v_pk_fma_f32 v[232:233], v[20:21], v[152:153], v[232:233]
	v_pk_fma_f32 v[234:235], v[22:23], v[154:155], v[234:235]
	v_pk_fma_f32 v[236:237], v[24:25], v[156:157], v[236:237]
	v_pk_fma_f32 v[238:239], v[26:27], v[158:159], v[238:239]
	v_pk_fma_f32 v[240:241], v[28:29], v[160:161], v[240:241]
	v_pk_fma_f32 v[242:243], v[30:31], v[162:163], v[242:243]
	v_pk_fma_f32 v[244:245], v[32:33], v[164:165], v[244:245]
	v_pk_fma_f32 v[230:231], v[34:35], v[166:167], v[230:231]
	v_pk_fma_f32 v[232:233], v[36:37], v[168:169], v[232:233]
	v_pk_fma_f32 v[234:235], v[38:39], v[170:171], v[234:235]
	v_pk_fma_f32 v[236:237], v[40:41], v[172:173], v[236:237]
	v_pk_fma_f32 v[238:239], v[42:43], v[174:175], v[238:239]
	v_pk_fma_f32 v[240:241], v[44:45], v[176:177], v[240:241]
	v_pk_fma_f32 v[242:243], v[46:47], v[178:179], v[242:243]
	v_pk_fma_f32 v[244:245], v[48:49], v[180:181], v[244:245]
	v_mul_f32_e32 v246, v230, v230
	v_mul_f32_e32 v247, v231, v231
	v_mul_f32_e32 v248, v232, v232
	v_mul_f32_e32 v249, v233, v233
	v_mul_f32_e32 v250, v234, v234
	v_mul_f32_e32 v251, v235, v235
	v_mul_f32_e32 v252, v236, v236
	v_mul_f32_e32 v253, v237, v237
	v_fma_f32 v246, v246, s67, v198
	v_fma_f32 v247, v247, s67, v198
	v_fma_f32 v248, v248, s67, v198
	v_fma_f32 v249, v249, s67, v198
	v_fma_f32 v250, v250, s67, v198
	v_fma_f32 v251, v251, s67, v198
	v_fma_f32 v252, v252, s67, v198
	v_fma_f32 v253, v253, s67, v198
	v_mul_f32_e32 v246, v230, v246
	v_mul_f32_e32 v247, v231, v247
	v_mul_f32_e32 v248, v232, v248
	v_mul_f32_e32 v249, v233, v249
	v_mul_f32_e32 v250, v234, v250
	v_mul_f32_e32 v251, v235, v251
	v_mul_f32_e32 v252, v236, v252
	v_mul_f32_e32 v253, v237, v253
	v_exp_f32_e32 v246, v246
	v_exp_f32_e32 v247, v247
	v_exp_f32_e32 v248, v248
	v_exp_f32_e32 v249, v249
	v_exp_f32_e32 v250, v250
	v_exp_f32_e32 v251, v251
	v_exp_f32_e32 v252, v252
	v_exp_f32_e32 v253, v253
	v_add_f32_e32 v246, 1.0, v246
	v_add_f32_e32 v247, 1.0, v247
	v_add_f32_e32 v248, 1.0, v248
	v_add_f32_e32 v249, 1.0, v249
	v_add_f32_e32 v250, 1.0, v250
	v_add_f32_e32 v251, 1.0, v251
	v_add_f32_e32 v252, 1.0, v252
	v_add_f32_e32 v253, 1.0, v253
	v_rcp_f32_e32 v246, v246
	v_rcp_f32_e32 v247, v247
	v_rcp_f32_e32 v248, v248
	v_rcp_f32_e32 v249, v249
	v_rcp_f32_e32 v250, v250
	v_rcp_f32_e32 v251, v251
	v_rcp_f32_e32 v252, v252
	v_rcp_f32_e32 v253, v253
	v_mul_f32_e32 v246, v230, v246
	v_mul_f32_e32 v247, v231, v247
	v_mul_f32_e32 v248, v232, v248
	v_mul_f32_e32 v249, v233, v249
	v_mul_f32_e32 v250, v234, v250
	v_mul_f32_e32 v251, v235, v251
	v_mul_f32_e32 v252, v236, v252
	v_mul_f32_e32 v253, v237, v253
	v_mul_f32_e32 v246, v246, v238
	v_mul_f32_e32 v247, v247, v239
	v_mul_f32_e32 v248, v248, v240
	v_mul_f32_e32 v249, v249, v241
	v_mul_f32_e32 v250, v250, v242
	v_mul_f32_e32 v251, v251, v243
	v_mul_f32_e32 v252, v252, v244
	v_mul_f32_e32 v253, v253, v245
	v_cvt_pk_bf16_f32 v190, v246, v247
	v_cvt_pk_bf16_f32 v191, v248, v249
	v_cvt_pk_bf16_f32 v192, v250, v251
	v_cvt_pk_bf16_f32 v193, v252, v253
	global_store_dwordx4 v144, v[190:193], s[22:23]
	v_add_u32_e32 v144, 0x1600, v144
	v_lshlrev_b32_e32 v214, 16, v106
	v_and_b32_e32 v215, s21, v106
	v_lshlrev_b32_e32 v216, 16, v107
	v_and_b32_e32 v217, s21, v107
	v_lshlrev_b32_e32 v218, 16, v108
	v_and_b32_e32 v219, s21, v108
	v_lshlrev_b32_e32 v220, 16, v109
	v_and_b32_e32 v221, s21, v109
	v_lshlrev_b32_e32 v222, 16, v110
	v_and_b32_e32 v223, s21, v110
	v_lshlrev_b32_e32 v224, 16, v111
	v_and_b32_e32 v225, s21, v111
	v_lshlrev_b32_e32 v226, 16, v112
	v_and_b32_e32 v227, s21, v112
	v_lshlrev_b32_e32 v228, 16, v113
	v_and_b32_e32 v229, s21, v113
	v_pk_fma_f32 v[230:231], v[2:3], v[150:151], v[50:51]
	v_pk_fma_f32 v[232:233], v[4:5], v[152:153], v[52:53]
	v_pk_fma_f32 v[234:235], v[6:7], v[154:155], v[54:55]
	v_pk_fma_f32 v[236:237], v[8:9], v[156:157], v[56:57]
	v_pk_fma_f32 v[238:239], v[10:11], v[158:159], v[58:59]
	v_pk_fma_f32 v[240:241], v[12:13], v[160:161], v[60:61]
	v_pk_fma_f32 v[242:243], v[14:15], v[162:163], v[62:63]
	v_pk_fma_f32 v[244:245], v[16:17], v[164:165], v[64:65]
	v_pk_fma_f32 v[230:231], v[18:19], v[166:167], v[230:231]
	v_pk_fma_f32 v[232:233], v[20:21], v[168:169], v[232:233]
	v_pk_fma_f32 v[234:235], v[22:23], v[170:171], v[234:235]
	v_pk_fma_f32 v[236:237], v[24:25], v[172:173], v[236:237]
	v_pk_fma_f32 v[238:239], v[26:27], v[174:175], v[238:239]
	v_pk_fma_f32 v[240:241], v[28:29], v[176:177], v[240:241]
	v_pk_fma_f32 v[242:243], v[30:31], v[178:179], v[242:243]
	v_pk_fma_f32 v[244:245], v[32:33], v[180:181], v[244:245]
	v_pk_fma_f32 v[230:231], v[34:35], v[214:215], v[230:231]
	v_pk_fma_f32 v[232:233], v[36:37], v[216:217], v[232:233]
	v_pk_fma_f32 v[234:235], v[38:39], v[218:219], v[234:235]
	v_pk_fma_f32 v[236:237], v[40:41], v[220:221], v[236:237]
	v_pk_fma_f32 v[238:239], v[42:43], v[222:223], v[238:239]
	v_pk_fma_f32 v[240:241], v[44:45], v[224:225], v[240:241]
	v_pk_fma_f32 v[242:243], v[46:47], v[226:227], v[242:243]
	v_pk_fma_f32 v[244:245], v[48:49], v[228:229], v[244:245]
	v_mul_f32_e32 v246, v230, v230
	v_mul_f32_e32 v247, v231, v231
	v_mul_f32_e32 v248, v232, v232
	v_mul_f32_e32 v249, v233, v233
	v_mul_f32_e32 v250, v234, v234
	v_mul_f32_e32 v251, v235, v235
	v_mul_f32_e32 v252, v236, v236
	v_mul_f32_e32 v253, v237, v237
	v_fma_f32 v246, v246, s67, v198
	v_fma_f32 v247, v247, s67, v198
; #define GAS __attribute__((address_space(1)))
;     ...
;         for (int i = 0; i < 8; ++i) {
;           const int row = (tid >> 4) + i * 32;
;           const int rg = g0 + cur_brow + row;
;           int t, b; const bool samp = rg >= NPROMPT;
;           if (!samp) { t = rg & (SEQ - 1); b = rg >> 11; } else { const int rs = rg - NPROMPT; t = rs & (DSEQ - 1); b = rs >> 6; }
;           if (t >= 2 && row < 2) continue;
;           float res[8];
; #pragma unroll
;           for (int h = 0; h < 2; ++h) {
;             const int c16 = h * 16 + ck;
;             float cur[8], p1[8], p2[8];
;             ld8(reinterpret_cast<const u16*>(st + row * 512 + ((c16 ^ (row & 31)) << 4)), cur);
;             if (t >= 1) ld8(reinterpret_cast<const u16*>(st + (row - 1) * 512 + ((c16 ^ ((row - 1) & 31)) << 4)), p1);
;             else if (samp) ld8f(p->cstate + ((size_t)b * 2 + 1) * UPW + ch + h * DFF, p1);
;             else { for (int k = 0; k < 8; ++k) p1[k] = 0.f; }
;             if (t >= 2) ld8(reinterpret_cast<const u16*>(st + (row - 2) * 512 + ((c16 ^ ((row - 2) & 31)) << 4)), p2);
;             else if (samp) ld8f(p->cstate + ((size_t)b * 2 + t) * UPW + ch + h * DFF, p2);
;             else { for (int k = 0; k < 8; ++k) p2[k] = 0.f; }
; #pragma unroll
;             for (int k = 0; k < 8; ++k) {
;               float cv = bb[h][k] + w0[h][k] * p2[k] + w1[h][k] * p1[k] + w2[h][k] * cur[k];
;               if (h == 0) res[k] = gelu_f(cv); else res[k] *= cv;
;             }
;           }
;           *(GAS uint4*)(FI + (size_t)(cur_brow + row) * DFF + ch) =
;               make_uint4(pack2(res[0], res[1]), pack2(res[2], res[3]), pack2(res[4], res[5]), pack2(res[6], res[7]));
	v_fma_f32 v248, v248, s67, v198
	v_fma_f32 v249, v249, s67, v198
	v_fma_f32 v250, v250, s67, v198
	v_fma_f32 v251, v251, s67, v198
	v_fma_f32 v252, v252, s67, v198
	v_fma_f32 v253, v253, s67, v198
	v_mul_f32_e32 v246, v230, v246
	v_mul_f32_e32 v247, v231, v247
	v_mul_f32_e32 v248, v232, v248
	v_mul_f32_e32 v249, v233, v249
	v_mul_f32_e32 v250, v234, v250
	v_mul_f32_e32 v251, v235, v251
	v_mul_f32_e32 v252, v236, v252
	v_mul_f32_e32 v253, v237, v253
	v_exp_f32_e32 v246, v246
	v_exp_f32_e32 v247, v247
	v_exp_f32_e32 v248, v248
	v_exp_f32_e32 v249, v249
	v_exp_f32_e32 v250, v250
	v_exp_f32_e32 v251, v251
	v_exp_f32_e32 v252, v252
	v_exp_f32_e32 v253, v253
	v_add_f32_e32 v246, 1.0, v246
	v_add_f32_e32 v247, 1.0, v247
	v_add_f32_e32 v248, 1.0, v248
	v_add_f32_e32 v249, 1.0, v249
	v_add_f32_e32 v250, 1.0, v250
	v_add_f32_e32 v251, 1.0, v251
	v_add_f32_e32 v252, 1.0, v252
	v_add_f32_e32 v253, 1.0, v253
	v_rcp_f32_e32 v246, v246
	v_rcp_f32_e32 v247, v247
	v_rcp_f32_e32 v248, v248
	v_rcp_f32_e32 v249, v249
	v_rcp_f32_e32 v250, v250
	v_rcp_f32_e32 v251, v251
	v_rcp_f32_e32 v252, v252
	v_rcp_f32_e32 v253, v253
	v_mul_f32_e32 v246, v230, v246
	v_mul_f32_e32 v247, v231, v247
	v_mul_f32_e32 v248, v232, v248
	v_mul_f32_e32 v249, v233, v249
	v_mul_f32_e32 v250, v234, v250
	v_mul_f32_e32 v251, v235, v251
	v_mul_f32_e32 v252, v236, v252
	v_mul_f32_e32 v253, v237, v253
	v_mul_f32_e32 v246, v246, v238
	v_mul_f32_e32 v247, v247, v239
	v_mul_f32_e32 v248, v248, v240
	v_mul_f32_e32 v249, v249, v241
	v_mul_f32_e32 v250, v250, v242
	v_mul_f32_e32 v251, v251, v243
	v_mul_f32_e32 v252, v252, v244
	v_mul_f32_e32 v253, v253, v245
	v_cvt_pk_bf16_f32 v190, v246, v247
	v_cvt_pk_bf16_f32 v191, v248, v249
	v_cvt_pk_bf16_f32 v192, v250, v251
	v_cvt_pk_bf16_f32 v193, v252, v253
	global_store_dwordx4 v144, v[190:193], s[22:23]
	v_add_u32_e32 v144, 0x1600, v144
	v_lshlrev_b32_e32 v150, 16, v114
	v_and_b32_e32 v151, s21, v114
	v_lshlrev_b32_e32 v152, 16, v115
	v_and_b32_e32 v153, s21, v115
	v_lshlrev_b32_e32 v154, 16, v116
	v_and_b32_e32 v155, s21, v116
	v_lshlrev_b32_e32 v156, 16, v117
	v_and_b32_e32 v157, s21, v117
	v_lshlrev_b32_e32 v158, 16, v118
	v_and_b32_e32 v159, s21, v118
	v_lshlrev_b32_e32 v160, 16, v119
	v_and_b32_e32 v161, s21, v119
	v_lshlrev_b32_e32 v162, 16, v120
	v_and_b32_e32 v163, s21, v120
	v_lshlrev_b32_e32 v164, 16, v121
	v_and_b32_e32 v165, s21, v121
	v_pk_fma_f32 v[230:231], v[2:3], v[166:167], v[50:51]
	v_pk_fma_f32 v[232:233], v[4:5], v[168:169], v[52:53]
	v_pk_fma_f32 v[234:235], v[6:7], v[170:171], v[54:55]
	v_pk_fma_f32 v[236:237], v[8:9], v[172:173], v[56:57]
	v_pk_fma_f32 v[238:239], v[10:11], v[174:175], v[58:59]
	v_pk_fma_f32 v[240:241], v[12:13], v[176:177], v[60:61]
	v_pk_fma_f32 v[242:243], v[14:15], v[178:179], v[62:63]
	v_pk_fma_f32 v[244:245], v[16:17], v[180:181], v[64:65]
	v_pk_fma_f32 v[230:231], v[18:19], v[214:215], v[230:231]
	v_pk_fma_f32 v[232:233], v[20:21], v[216:217], v[232:233]
	v_pk_fma_f32 v[234:235], v[22:23], v[218:219], v[234:235]
	v_pk_fma_f32 v[236:237], v[24:25], v[220:221], v[236:237]
	v_pk_fma_f32 v[238:239], v[26:27], v[222:223], v[238:239]
	v_pk_fma_f32 v[240:241], v[28:29], v[224:225], v[240:241]
	v_pk_fma_f32 v[242:243], v[30:31], v[226:227], v[242:243]
	v_pk_fma_f32 v[244:245], v[32:33], v[228:229], v[244:245]
	v_pk_fma_f32 v[230:231], v[34:35], v[150:151], v[230:231]
	v_pk_fma_f32 v[232:233], v[36:37], v[152:153], v[232:233]
	v_pk_fma_f32 v[234:235], v[38:39], v[154:155], v[234:235]
	v_pk_fma_f32 v[236:237], v[40:41], v[156:157], v[236:237]
	v_pk_fma_f32 v[238:239], v[42:43], v[158:159], v[238:239]
	v_pk_fma_f32 v[240:241], v[44:45], v[160:161], v[240:241]
	v_pk_fma_f32 v[242:243], v[46:47], v[162:163], v[242:243]
	v_pk_fma_f32 v[244:245], v[48:49], v[164:165], v[244:245]
	v_mul_f32_e32 v246, v230, v230
	v_mul_f32_e32 v247, v231, v231
	v_mul_f32_e32 v248, v232, v232
	v_mul_f32_e32 v249, v233, v233
	v_mul_f32_e32 v250, v234, v234
	v_mul_f32_e32 v251, v235, v235
	v_mul_f32_e32 v252, v236, v236
	v_mul_f32_e32 v253, v237, v237
	v_fma_f32 v246, v246, s67, v198
	v_fma_f32 v247, v247, s67, v198
	v_fma_f32 v248, v248, s67, v198
	v_fma_f32 v249, v249, s67, v198
	v_fma_f32 v250, v250, s67, v198
	v_fma_f32 v251, v251, s67, v198
	v_fma_f32 v252, v252, s67, v198
	v_fma_f32 v253, v253, s67, v198
	v_mul_f32_e32 v246, v230, v246
	v_mul_f32_e32 v247, v231, v247
	v_mul_f32_e32 v248, v232, v248
	v_mul_f32_e32 v249, v233, v249
	v_mul_f32_e32 v250, v234, v250
	v_mul_f32_e32 v251, v235, v251
	v_mul_f32_e32 v252, v236, v252
	v_mul_f32_e32 v253, v237, v253
	v_exp_f32_e32 v246, v246
	v_exp_f32_e32 v247, v247
	v_exp_f32_e32 v248, v248
	v_exp_f32_e32 v249, v249
	v_exp_f32_e32 v250, v250
	v_exp_f32_e32 v251, v251
	v_exp_f32_e32 v252, v252
	v_exp_f32_e32 v253, v253
	v_add_f32_e32 v246, 1.0, v246
	v_add_f32_e32 v247, 1.0, v247
	v_add_f32_e32 v248, 1.0, v248
	v_add_f32_e32 v249, 1.0, v249
	v_add_f32_e32 v250, 1.0, v250
	v_add_f32_e32 v251, 1.0, v251
	v_add_f32_e32 v252, 1.0, v252
	v_add_f32_e32 v253, 1.0, v253
	v_rcp_f32_e32 v246, v246
	v_rcp_f32_e32 v247, v247
	v_rcp_f32_e32 v248, v248
	v_rcp_f32_e32 v249, v249
	v_rcp_f32_e32 v250, v250
	v_rcp_f32_e32 v251, v251
	v_rcp_f32_e32 v252, v252
	v_rcp_f32_e32 v253, v253
	v_mul_f32_e32 v246, v230, v246
	v_mul_f32_e32 v247, v231, v247
	v_mul_f32_e32 v248, v232, v248
	v_mul_f32_e32 v249, v233, v249
	v_mul_f32_e32 v250, v234, v250
	v_mul_f32_e32 v251, v235, v251
	v_mul_f32_e32 v252, v236, v252
	v_mul_f32_e32 v253, v237, v253
	v_mul_f32_e32 v246, v246, v238
	v_mul_f32_e32 v247, v247, v239
	v_mul_f32_e32 v248, v248, v240
	v_mul_f32_e32 v249, v249, v241
	v_mul_f32_e32 v250, v250, v242
; #define GAS __attribute__((address_space(1)))
;     ...
;         for (int i = 0; i < 8; ++i) {
;           const int row = (tid >> 4) + i * 32;
;           const int rg = g0 + cur_brow + row;
;           int t, b; const bool samp = rg >= NPROMPT;
;           if (!samp) { t = rg & (SEQ - 1); b = rg >> 11; } else { const int rs = rg - NPROMPT; t = rs & (DSEQ - 1); b = rs >> 6; }
;           if (t >= 2 && row < 2) continue;
;           float res[8];
; #pragma unroll
;           for (int h = 0; h < 2; ++h) {
;             const int c16 = h * 16 + ck;
;             float cur[8], p1[8], p2[8];
;             ld8(reinterpret_cast<const u16*>(st + row * 512 + ((c16 ^ (row & 31)) << 4)), cur);
;             if (t >= 1) ld8(reinterpret_cast<const u16*>(st + (row - 1) * 512 + ((c16 ^ ((row - 1) & 31)) << 4)), p1);
;             else if (samp) ld8f(p->cstate + ((size_t)b * 2 + 1) * UPW + ch + h * DFF, p1);
;             else { for (int k = 0; k < 8; ++k) p1[k] = 0.f; }
;             if (t >= 2) ld8(reinterpret_cast<const u16*>(st + (row - 2) * 512 + ((c16 ^ ((row - 2) & 31)) << 4)), p2);
;             else if (samp) ld8f(p->cstate + ((size_t)b * 2 + t) * UPW + ch + h * DFF, p2);
;             else { for (int k = 0; k < 8; ++k) p2[k] = 0.f; }
; #pragma unroll
;             for (int k = 0; k < 8; ++k) {
;               float cv = bb[h][k] + w0[h][k] * p2[k] + w1[h][k] * p1[k] + w2[h][k] * cur[k];
;               if (h == 0) res[k] = gelu_f(cv); else res[k] *= cv;
;             }
;           }
;           *(GAS uint4*)(FI + (size_t)(cur_brow + row) * DFF + ch) =
;               make_uint4(pack2(res[0], res[1]), pack2(res[2], res[3]), pack2(res[4], res[5]), pack2(res[6], res[7]));
	v_mul_f32_e32 v251, v251, v243
	v_mul_f32_e32 v252, v252, v244
	v_mul_f32_e32 v253, v253, v245
	v_cvt_pk_bf16_f32 v190, v246, v247
	v_cvt_pk_bf16_f32 v191, v248, v249
	v_cvt_pk_bf16_f32 v192, v250, v251
	v_cvt_pk_bf16_f32 v193, v252, v253
	global_store_dwordx4 v144, v[190:193], s[22:23]
	v_add_u32_e32 v144, 0x1600, v144
	v_lshlrev_b32_e32 v166, 16, v122
	v_and_b32_e32 v167, s21, v122
	v_lshlrev_b32_e32 v168, 16, v123
	v_and_b32_e32 v169, s21, v123
	v_lshlrev_b32_e32 v170, 16, v124
	v_and_b32_e32 v171, s21, v124
	v_lshlrev_b32_e32 v172, 16, v125
	v_and_b32_e32 v173, s21, v125
	v_lshlrev_b32_e32 v174, 16, v126
	v_and_b32_e32 v175, s21, v126
	v_lshlrev_b32_e32 v176, 16, v127
	v_and_b32_e32 v177, s21, v127
	v_lshlrev_b32_e32 v178, 16, v128
	v_and_b32_e32 v179, s21, v128
	v_lshlrev_b32_e32 v180, 16, v129
	v_and_b32_e32 v181, s21, v129
	v_pk_fma_f32 v[230:231], v[2:3], v[214:215], v[50:51]
	v_pk_fma_f32 v[232:233], v[4:5], v[216:217], v[52:53]
	v_pk_fma_f32 v[234:235], v[6:7], v[218:219], v[54:55]
	v_pk_fma_f32 v[236:237], v[8:9], v[220:221], v[56:57]
	v_pk_fma_f32 v[238:239], v[10:11], v[222:223], v[58:59]
	v_pk_fma_f32 v[240:241], v[12:13], v[224:225], v[60:61]
	v_pk_fma_f32 v[242:243], v[14:15], v[226:227], v[62:63]
	v_pk_fma_f32 v[244:245], v[16:17], v[228:229], v[64:65]
	v_pk_fma_f32 v[230:231], v[18:19], v[150:151], v[230:231]
	v_pk_fma_f32 v[232:233], v[20:21], v[152:153], v[232:233]
	v_pk_fma_f32 v[234:235], v[22:23], v[154:155], v[234:235]
	v_pk_fma_f32 v[236:237], v[24:25], v[156:157], v[236:237]
	v_pk_fma_f32 v[238:239], v[26:27], v[158:159], v[238:239]
	v_pk_fma_f32 v[240:241], v[28:29], v[160:161], v[240:241]
	v_pk_fma_f32 v[242:243], v[30:31], v[162:163], v[242:243]
	v_pk_fma_f32 v[244:245], v[32:33], v[164:165], v[244:245]
	v_pk_fma_f32 v[230:231], v[34:35], v[166:167], v[230:231]
	v_pk_fma_f32 v[232:233], v[36:37], v[168:169], v[232:233]
	v_pk_fma_f32 v[234:235], v[38:39], v[170:171], v[234:235]
	v_pk_fma_f32 v[236:237], v[40:41], v[172:173], v[236:237]
	v_pk_fma_f32 v[238:239], v[42:43], v[174:175], v[238:239]
	v_pk_fma_f32 v[240:241], v[44:45], v[176:177], v[240:241]
	v_pk_fma_f32 v[242:243], v[46:47], v[178:179], v[242:243]
	v_pk_fma_f32 v[244:245], v[48:49], v[180:181], v[244:245]
	v_mul_f32_e32 v246, v230, v230
	v_mul_f32_e32 v247, v231, v231
	v_mul_f32_e32 v248, v232, v232
	v_mul_f32_e32 v249, v233, v233
	v_mul_f32_e32 v250, v234, v234
	v_mul_f32_e32 v251, v235, v235
	v_mul_f32_e32 v252, v236, v236
	v_mul_f32_e32 v253, v237, v237
	v_fma_f32 v246, v246, s67, v198
	v_fma_f32 v247, v247, s67, v198
	v_fma_f32 v248, v248, s67, v198
	v_fma_f32 v249, v249, s67, v198
	v_fma_f32 v250, v250, s67, v198
	v_fma_f32 v251, v251, s67, v198
	v_fma_f32 v252, v252, s67, v198
	v_fma_f32 v253, v253, s67, v198
	v_mul_f32_e32 v246, v230, v246
	v_mul_f32_e32 v247, v231, v247
	v_mul_f32_e32 v248, v232, v248
	v_mul_f32_e32 v249, v233, v249
	v_mul_f32_e32 v250, v234, v250
	v_mul_f32_e32 v251, v235, v251
	v_mul_f32_e32 v252, v236, v252
	v_mul_f32_e32 v253, v237, v253
	v_exp_f32_e32 v246, v246
	v_exp_f32_e32 v247, v247
	v_exp_f32_e32 v248, v248
	v_exp_f32_e32 v249, v249
	v_exp_f32_e32 v250, v250
	v_exp_f32_e32 v251, v251
	v_exp_f32_e32 v252, v252
	v_exp_f32_e32 v253, v253
	v_add_f32_e32 v246, 1.0, v246
	v_add_f32_e32 v247, 1.0, v247
	v_add_f32_e32 v248, 1.0, v248
	v_add_f32_e32 v249, 1.0, v249
	v_add_f32_e32 v250, 1.0, v250
	v_add_f32_e32 v251, 1.0, v251
	v_add_f32_e32 v252, 1.0, v252
	v_add_f32_e32 v253, 1.0, v253
	v_rcp_f32_e32 v246, v246
	v_rcp_f32_e32 v247, v247
	v_rcp_f32_e32 v248, v248
	v_rcp_f32_e32 v249, v249
	v_rcp_f32_e32 v250, v250
	v_rcp_f32_e32 v251, v251
	v_rcp_f32_e32 v252, v252
	v_rcp_f32_e32 v253, v253
	v_mul_f32_e32 v246, v230, v246
	v_mul_f32_e32 v247, v231, v247
	v_mul_f32_e32 v248, v232, v248
	v_mul_f32_e32 v249, v233, v249
	v_mul_f32_e32 v250, v234, v250
	v_mul_f32_e32 v251, v235, v251
	v_mul_f32_e32 v252, v236, v252
	v_mul_f32_e32 v253, v237, v253
	v_mul_f32_e32 v246, v246, v238
	v_mul_f32_e32 v247, v247, v239
	v_mul_f32_e32 v248, v248, v240
	v_mul_f32_e32 v249, v249, v241
	v_mul_f32_e32 v250, v250, v242
	v_mul_f32_e32 v251, v251, v243
	v_mul_f32_e32 v252, v252, v244
	v_mul_f32_e32 v253, v253, v245
	v_cvt_pk_bf16_f32 v190, v246, v247
	v_cvt_pk_bf16_f32 v191, v248, v249
	v_cvt_pk_bf16_f32 v192, v250, v251
	v_cvt_pk_bf16_f32 v193, v252, v253
	global_store_dwordx4 v144, v[190:193], s[22:23]
	v_add_u32_e32 v144, 0x1600, v144
	v_lshlrev_b32_e32 v214, 16, v66
	v_and_b32_e32 v215, s21, v66
	v_lshlrev_b32_e32 v216, 16, v67
	v_and_b32_e32 v217, s21, v67
	v_lshlrev_b32_e32 v218, 16, v68
	v_and_b32_e32 v219, s21, v68
	v_lshlrev_b32_e32 v220, 16, v69
	v_and_b32_e32 v221, s21, v69
	v_lshlrev_b32_e32 v222, 16, v70
	v_and_b32_e32 v223, s21, v70
	v_lshlrev_b32_e32 v224, 16, v71
	v_and_b32_e32 v225, s21, v71
	v_lshlrev_b32_e32 v226, 16, v72
	v_and_b32_e32 v227, s21, v72
	v_lshlrev_b32_e32 v228, 16, v73
	v_and_b32_e32 v229, s21, v73
	v_pk_fma_f32 v[230:231], v[2:3], v[150:151], v[50:51]
	v_pk_fma_f32 v[232:233], v[4:5], v[152:153], v[52:53]
	v_pk_fma_f32 v[234:235], v[6:7], v[154:155], v[54:55]
	v_pk_fma_f32 v[236:237], v[8:9], v[156:157], v[56:57]
	v_pk_fma_f32 v[238:239], v[10:11], v[158:159], v[58:59]
	v_pk_fma_f32 v[240:241], v[12:13], v[160:161], v[60:61]
	v_pk_fma_f32 v[242:243], v[14:15], v[162:163], v[62:63]
	v_pk_fma_f32 v[244:245], v[16:17], v[164:165], v[64:65]
	v_pk_fma_f32 v[230:231], v[18:19], v[166:167], v[230:231]
	v_pk_fma_f32 v[232:233], v[20:21], v[168:169], v[232:233]
	v_pk_fma_f32 v[234:235], v[22:23], v[170:171], v[234:235]
	v_pk_fma_f32 v[236:237], v[24:25], v[172:173], v[236:237]
	v_pk_fma_f32 v[238:239], v[26:27], v[174:175], v[238:239]
; #define GAS __attribute__((address_space(1)))
;     ...
;         for (int i = 0; i < 8; ++i) {
;           const int row = (tid >> 4) + i * 32;
;           const int rg = g0 + cur_brow + row;
;           int t, b; const bool samp = rg >= NPROMPT;
;           if (!samp) { t = rg & (SEQ - 1); b = rg >> 11; } else { const int rs = rg - NPROMPT; t = rs & (DSEQ - 1); b = rs >> 6; }
;           if (t >= 2 && row < 2) continue;
;           float res[8];
; #pragma unroll
;           for (int h = 0; h < 2; ++h) {
;             const int c16 = h * 16 + ck;
;             float cur[8], p1[8], p2[8];
;             ld8(reinterpret_cast<const u16*>(st + row * 512 + ((c16 ^ (row & 31)) << 4)), cur);
;             if (t >= 1) ld8(reinterpret_cast<const u16*>(st + (row - 1) * 512 + ((c16 ^ ((row - 1) & 31)) << 4)), p1);
;             else if (samp) ld8f(p->cstate + ((size_t)b * 2 + 1) * UPW + ch + h * DFF, p1);
;             else { for (int k = 0; k < 8; ++k) p1[k] = 0.f; }
;             if (t >= 2) ld8(reinterpret_cast<const u16*>(st + (row - 2) * 512 + ((c16 ^ ((row - 2) & 31)) << 4)), p2);
;             else if (samp) ld8f(p->cstate + ((size_t)b * 2 + t) * UPW + ch + h * DFF, p2);
;             else { for (int k = 0; k < 8; ++k) p2[k] = 0.f; }
; #pragma unroll
;             for (int k = 0; k < 8; ++k) {
;               float cv = bb[h][k] + w0[h][k] * p2[k] + w1[h][k] * p1[k] + w2[h][k] * cur[k];
;               if (h == 0) res[k] = gelu_f(cv); else res[k] *= cv;
;             }
;           }
;           *(GAS uint4*)(FI + (size_t)(cur_brow + row) * DFF + ch) =
;               make_uint4(pack2(res[0], res[1]), pack2(res[2], res[3]), pack2(res[4], res[5]), pack2(res[6], res[7]));
	v_pk_fma_f32 v[240:241], v[28:29], v[176:177], v[240:241]
	v_pk_fma_f32 v[242:243], v[30:31], v[178:179], v[242:243]
	v_pk_fma_f32 v[244:245], v[32:33], v[180:181], v[244:245]
	v_pk_fma_f32 v[230:231], v[34:35], v[214:215], v[230:231]
	v_pk_fma_f32 v[232:233], v[36:37], v[216:217], v[232:233]
	v_pk_fma_f32 v[234:235], v[38:39], v[218:219], v[234:235]
	v_pk_fma_f32 v[236:237], v[40:41], v[220:221], v[236:237]
	v_pk_fma_f32 v[238:239], v[42:43], v[222:223], v[238:239]
	v_pk_fma_f32 v[240:241], v[44:45], v[224:225], v[240:241]
	v_pk_fma_f32 v[242:243], v[46:47], v[226:227], v[242:243]
	v_pk_fma_f32 v[244:245], v[48:49], v[228:229], v[244:245]
	v_mul_f32_e32 v246, v230, v230
	v_mul_f32_e32 v247, v231, v231
	v_mul_f32_e32 v248, v232, v232
	v_mul_f32_e32 v249, v233, v233
	v_mul_f32_e32 v250, v234, v234
	v_mul_f32_e32 v251, v235, v235
	v_mul_f32_e32 v252, v236, v236
	v_mul_f32_e32 v253, v237, v237
	v_fma_f32 v246, v246, s67, v198
	v_fma_f32 v247, v247, s67, v198
	v_fma_f32 v248, v248, s67, v198
	v_fma_f32 v249, v249, s67, v198
	v_fma_f32 v250, v250, s67, v198
	v_fma_f32 v251, v251, s67, v198
	v_fma_f32 v252, v252, s67, v198
	v_fma_f32 v253, v253, s67, v198
	v_mul_f32_e32 v246, v230, v246
	v_mul_f32_e32 v247, v231, v247
	v_mul_f32_e32 v248, v232, v248
	v_mul_f32_e32 v249, v233, v249
	v_mul_f32_e32 v250, v234, v250
	v_mul_f32_e32 v251, v235, v251
	v_mul_f32_e32 v252, v236, v252
	v_mul_f32_e32 v253, v237, v253
	v_exp_f32_e32 v246, v246
	v_exp_f32_e32 v247, v247
	v_exp_f32_e32 v248, v248
	v_exp_f32_e32 v249, v249
	v_exp_f32_e32 v250, v250
	v_exp_f32_e32 v251, v251
	v_exp_f32_e32 v252, v252
	v_exp_f32_e32 v253, v253
	v_add_f32_e32 v246, 1.0, v246
	v_add_f32_e32 v247, 1.0, v247
	v_add_f32_e32 v248, 1.0, v248
	v_add_f32_e32 v249, 1.0, v249
	v_add_f32_e32 v250, 1.0, v250
	v_add_f32_e32 v251, 1.0, v251
	v_add_f32_e32 v252, 1.0, v252
	v_add_f32_e32 v253, 1.0, v253
	v_rcp_f32_e32 v246, v246
	v_rcp_f32_e32 v247, v247
	v_rcp_f32_e32 v248, v248
	v_rcp_f32_e32 v249, v249
	v_rcp_f32_e32 v250, v250
	v_rcp_f32_e32 v251, v251
	v_rcp_f32_e32 v252, v252
	v_rcp_f32_e32 v253, v253
	v_mul_f32_e32 v246, v230, v246
	v_mul_f32_e32 v247, v231, v247
	v_mul_f32_e32 v248, v232, v248
	v_mul_f32_e32 v249, v233, v249
	v_mul_f32_e32 v250, v234, v250
	v_mul_f32_e32 v251, v235, v251
	v_mul_f32_e32 v252, v236, v252
	v_mul_f32_e32 v253, v237, v253
	v_mul_f32_e32 v246, v246, v238
	v_mul_f32_e32 v247, v247, v239
	v_mul_f32_e32 v248, v248, v240
	v_mul_f32_e32 v249, v249, v241
	v_mul_f32_e32 v250, v250, v242
	v_mul_f32_e32 v251, v251, v243
	v_mul_f32_e32 v252, v252, v244
	v_mul_f32_e32 v253, v253, v245
	v_cvt_pk_bf16_f32 v190, v246, v247
	v_cvt_pk_bf16_f32 v191, v248, v249
	v_cvt_pk_bf16_f32 v192, v250, v251
	v_cvt_pk_bf16_f32 v193, v252, v253
	global_store_dwordx4 v144, v[190:193], s[22:23]
	v_add_u32_e32 v144, 0x1600, v144
	v_lshlrev_b32_e32 v150, 16, v74
	v_and_b32_e32 v151, s21, v74
	v_lshlrev_b32_e32 v152, 16, v75
	v_and_b32_e32 v153, s21, v75
	v_lshlrev_b32_e32 v154, 16, v76
	v_and_b32_e32 v155, s21, v76
	v_lshlrev_b32_e32 v156, 16, v77
	v_and_b32_e32 v157, s21, v77
	v_lshlrev_b32_e32 v158, 16, v78
	v_and_b32_e32 v159, s21, v78
	v_lshlrev_b32_e32 v160, 16, v79
	v_and_b32_e32 v161, s21, v79
	v_lshlrev_b32_e32 v162, 16, v80
	v_and_b32_e32 v163, s21, v80
	v_lshlrev_b32_e32 v164, 16, v81
	v_and_b32_e32 v165, s21, v81
	v_pk_fma_f32 v[230:231], v[2:3], v[166:167], v[50:51]
	v_pk_fma_f32 v[232:233], v[4:5], v[168:169], v[52:53]
	v_pk_fma_f32 v[234:235], v[6:7], v[170:171], v[54:55]
	v_pk_fma_f32 v[236:237], v[8:9], v[172:173], v[56:57]
	v_pk_fma_f32 v[238:239], v[10:11], v[174:175], v[58:59]
	v_pk_fma_f32 v[240:241], v[12:13], v[176:177], v[60:61]
	v_pk_fma_f32 v[242:243], v[14:15], v[178:179], v[62:63]
	v_pk_fma_f32 v[244:245], v[16:17], v[180:181], v[64:65]
	v_pk_fma_f32 v[230:231], v[18:19], v[214:215], v[230:231]
	v_pk_fma_f32 v[232:233], v[20:21], v[216:217], v[232:233]
	v_pk_fma_f32 v[234:235], v[22:23], v[218:219], v[234:235]
	v_pk_fma_f32 v[236:237], v[24:25], v[220:221], v[236:237]
	v_pk_fma_f32 v[238:239], v[26:27], v[222:223], v[238:239]
	v_pk_fma_f32 v[240:241], v[28:29], v[224:225], v[240:241]
	v_pk_fma_f32 v[242:243], v[30:31], v[226:227], v[242:243]
	v_pk_fma_f32 v[244:245], v[32:33], v[228:229], v[244:245]
	v_pk_fma_f32 v[230:231], v[34:35], v[150:151], v[230:231]
	v_pk_fma_f32 v[232:233], v[36:37], v[152:153], v[232:233]
	v_pk_fma_f32 v[234:235], v[38:39], v[154:155], v[234:235]
	v_pk_fma_f32 v[236:237], v[40:41], v[156:157], v[236:237]
	v_pk_fma_f32 v[238:239], v[42:43], v[158:159], v[238:239]
	v_pk_fma_f32 v[240:241], v[44:45], v[160:161], v[240:241]
	v_pk_fma_f32 v[242:243], v[46:47], v[162:163], v[242:243]
	v_pk_fma_f32 v[244:245], v[48:49], v[164:165], v[244:245]
	v_mul_f32_e32 v246, v230, v230
	v_mul_f32_e32 v247, v231, v231
	v_mul_f32_e32 v248, v232, v232
	v_mul_f32_e32 v249, v233, v233
	v_mul_f32_e32 v250, v234, v234
	v_mul_f32_e32 v251, v235, v235
	v_mul_f32_e32 v252, v236, v236
	v_mul_f32_e32 v253, v237, v237
	v_fma_f32 v246, v246, s67, v198
	v_fma_f32 v247, v247, s67, v198
	v_fma_f32 v248, v248, s67, v198
	v_fma_f32 v249, v249, s67, v198
	v_fma_f32 v250, v250, s67, v198
	v_fma_f32 v251, v251, s67, v198
	v_fma_f32 v252, v252, s67, v198
	v_fma_f32 v253, v253, s67, v198
	v_mul_f32_e32 v246, v230, v246
	v_mul_f32_e32 v247, v231, v247
	v_mul_f32_e32 v248, v232, v248
	v_mul_f32_e32 v249, v233, v249
	v_mul_f32_e32 v250, v234, v250
	v_mul_f32_e32 v251, v235, v251
	v_mul_f32_e32 v252, v236, v252
	v_mul_f32_e32 v253, v237, v253
	v_exp_f32_e32 v246, v246
	v_exp_f32_e32 v247, v247
	v_exp_f32_e32 v248, v248
	v_exp_f32_e32 v249, v249
	v_exp_f32_e32 v250, v250
	v_exp_f32_e32 v251, v251
	v_exp_f32_e32 v252, v252
	v_exp_f32_e32 v253, v253
	v_add_f32_e32 v246, 1.0, v246
	v_add_f32_e32 v247, 1.0, v247
	v_add_f32_e32 v248, 1.0, v248
	v_add_f32_e32 v249, 1.0, v249
	v_add_f32_e32 v250, 1.0, v250
	v_add_f32_e32 v251, 1.0, v251
	v_add_f32_e32 v252, 1.0, v252
	v_add_f32_e32 v253, 1.0, v253
	v_rcp_f32_e32 v246, v246
	v_rcp_f32_e32 v247, v247
	v_rcp_f32_e32 v248, v248
	v_rcp_f32_e32 v249, v249
	v_rcp_f32_e32 v250, v250
	v_rcp_f32_e32 v251, v251
	v_rcp_f32_e32 v252, v252
	v_rcp_f32_e32 v253, v253
	v_mul_f32_e32 v246, v230, v246
	v_mul_f32_e32 v247, v231, v247
	v_mul_f32_e32 v248, v232, v248
	v_mul_f32_e32 v249, v233, v249
	v_mul_f32_e32 v250, v234, v250
	v_mul_f32_e32 v251, v235, v251
	v_mul_f32_e32 v252, v236, v252
	v_mul_f32_e32 v253, v237, v253
	v_mul_f32_e32 v246, v246, v238
	v_mul_f32_e32 v247, v247, v239
	v_mul_f32_e32 v248, v248, v240
	v_mul_f32_e32 v249, v249, v241
	v_mul_f32_e32 v250, v250, v242
	v_mul_f32_e32 v251, v251, v243
	v_mul_f32_e32 v252, v252, v244
	v_mul_f32_e32 v253, v253, v245
	v_cvt_pk_bf16_f32 v190, v246, v247
	v_cvt_pk_bf16_f32 v191, v248, v249
	v_cvt_pk_bf16_f32 v192, v250, v251
	v_cvt_pk_bf16_f32 v193, v252, v253
	global_store_dwordx4 v144, v[190:193], s[22:23]
	s_branch .LBB0_934
